# weight-conversion item loops (P0 W_in, P8 W_up): the last partial round of items is dealt one per wave across all workgroups (wave*256 + blockIdx) instead of 8 per workgroup on the first 20 / 192 CUs
# speedup vs baseline: 1.0066x; 1.0038x over previous
; #define LAS __attribute__((address_space(3)))
; #define LDS_WAIT() asm volatile("s_waitcnt lgkmcnt(0)" ::: "memory")
; __device__ __forceinline__ unsigned pk2(float lo, float hi) { return pg8::cvt_pk_bf16(lo, hi); }
; __device__ __forceinline__ void tr_store(const TJob& j, const f32x4 (&v)[16], LAS float* scr, int lane) {
;     const int k0 = 64 * j.kb, nq = lane & 15, kr = lane >> 4;
; #pragma unroll
;     for (int i = 0; i < 16; ++i) { LAS float* d = scr + (4 * i + kr) * TP + 4 * nq; const float sc = j.kscale ? j.kscale[k0 + 4 * i + kr] : 1.f; d[0] = v[i].x * sc; d[1] = v[i].y * sc; d[2] = v[i].z * sc; d[3] = v[i].w * sc; }
;     LDS_WAIT(); asm volatile("" ::: "memory");
;     const int c = lane & 7;
; #pragma unroll
;     for (int jj = 0; jj < 8; ++jj) { const int n = (lane >> 3) + 8 * jj; const LAS float* q = scr + (8 * c) * TP + n; const int nd = j.perm ? 32 * ((n >> 4) & 1) + 8 * ((n >> 2) & 3) + 4 * (n >> 5) + (n & 3) : n;
;         v4u o; o.x = pk2(q[0 * TP], q[1 * TP]); o.y = pk2(q[2 * TP], q[3 * TP]); o.z = pk2(q[4 * TP], q[5 * TP]); o.w = pk2(q[6 * TP], q[7 * TP]);
;         *(v4u*)(j.WT + (size_t)(j.drow0 + nd) * j.K + k0 + 8 * c) = o; }
;     LDS_WAIT(); asm volatile("" ::: "memory");
; }
.LBB0_12:
	v_add_u32_e32 v147, 0x410, v145
	v_add_u32_e32 v148, 0x418, v145
	v_add_u32_e32 v149, 0x820, v145
	v_add_u32_e32 v150, 0x828, v145
	v_add_u32_e32 v151, 0xc30, v145
	v_add_u32_e32 v152, 0xc38, v145
	v_add_u32_e32 v153, 0x1040, v145
	v_add_u32_e32 v154, 0x1048, v145
	v_add_u32_e32 v155, 0x1450, v145
	v_add_u32_e32 v156, 0x1458, v145
	v_add_u32_e32 v157, 0x1860, v145
	v_add_u32_e32 v158, 0x1868, v145
	v_add_u32_e32 v159, 0x1c70, v145
	v_add_u32_e32 v160, 0x1c78, v145
	v_add_u32_e32 v161, 0x2080, v145
	v_add_u32_e32 v162, 0x2088, v145
	v_add_u32_e32 v163, 0x2490, v145
	v_add_u32_e32 v164, 0x2498, v145
	v_add_u32_e32 v165, 0x28a0, v145
	v_add_u32_e32 v166, 0x28a8, v145
	v_add_u32_e32 v167, 0x2cb0, v145
	v_add_u32_e32 v168, 0x2cb8, v145
	v_add_u32_e32 v169, 0x30c0, v145
	v_add_u32_e32 v170, 0x30c8, v145
	v_add_u32_e32 v171, 0x34d0, v145
	v_add_u32_e32 v172, 0x34d8, v145
	v_add_u32_e32 v173, 0x38e0, v145
	v_add_u32_e32 v174, 0x38e8, v145
	v_add_u32_e32 v175, 0x3cf0, v145
	v_add_u32_e32 v176, 0x3cf8, v145
	s_waitcnt vmcnt(15)
	ds_write2_b32 v145, v2, v3 offset1:1
	ds_write2_b32 v145, v4, v5 offset0:2 offset1:3
	s_waitcnt vmcnt(14)
	ds_write2_b32 v147, v6, v7 offset1:1
	ds_write2_b32 v148, v8, v9 offset1:1
	s_waitcnt vmcnt(13)
	ds_write2_b32 v149, v10, v11 offset1:1
	ds_write2_b32 v150, v12, v13 offset1:1
	s_waitcnt vmcnt(12)
	ds_write2_b32 v151, v14, v15 offset1:1
	ds_write2_b32 v152, v16, v17 offset1:1
	s_waitcnt vmcnt(11)
	ds_write2_b32 v153, v18, v19 offset1:1
	ds_write2_b32 v154, v20, v21 offset1:1
	s_waitcnt vmcnt(10)
	ds_write2_b32 v155, v22, v23 offset1:1
	ds_write2_b32 v156, v24, v25 offset1:1
	s_waitcnt vmcnt(9)
	ds_write2_b32 v157, v34, v35 offset1:1
	ds_write2_b32 v158, v36, v37 offset1:1
	s_waitcnt vmcnt(8)
	ds_write2_b32 v159, v38, v39 offset1:1
	ds_write2_b32 v160, v40, v41 offset1:1
	s_waitcnt vmcnt(7)
	ds_write2_b32 v161, v50, v51 offset1:1
	ds_write2_b32 v162, v52, v53 offset1:1
	s_waitcnt vmcnt(6)
	ds_write2_b32 v163, v54, v55 offset1:1
	ds_write2_b32 v164, v56, v57 offset1:1
	s_waitcnt vmcnt(5)
	ds_write2_b32 v165, v66, v67 offset1:1
	ds_write2_b32 v166, v68, v69 offset1:1
	s_waitcnt vmcnt(4)
	ds_write2_b32 v167, v70, v71 offset1:1
	ds_write2_b32 v168, v72, v73 offset1:1
	s_waitcnt vmcnt(3)
	ds_write2_b32 v169, v82, v83 offset1:1
	ds_write2_b32 v170, v84, v85 offset1:1
	s_waitcnt vmcnt(2)
	ds_write2_b32 v171, v86, v87 offset1:1
	ds_write2_b32 v172, v88, v89 offset1:1
	s_waitcnt vmcnt(1)
	ds_write2_b32 v173, v98, v99 offset1:1
	ds_write2_b32 v174, v100, v101 offset1:1
	s_waitcnt vmcnt(0)
	ds_write2_b32 v175, v102, v103 offset1:1
	ds_write2_b32 v176, v104, v105 offset1:1
	s_waitcnt lgkmcnt(0)
	ds_read2_b32 v[178:179], v137 offset1:65
	s_waitcnt lgkmcnt(0)
	v_cvt_pk_bf16_f32 v178, v178, v179
	ds_read2_b32 v[180:181], v137 offset0:130 offset1:195
	v_add_u32_e32 v146, 0x400, v137
	s_waitcnt lgkmcnt(0)
	v_cvt_pk_bf16_f32 v179, v180, v181
	ds_read2_b32 v[180:181], v146 offset0:4 offset1:69
	s_waitcnt lgkmcnt(0)
	v_cvt_pk_bf16_f32 v180, v180, v181
	ds_read2_b32 v[182:183], v146 offset0:134 offset1:199
	s_waitcnt lgkmcnt(0)
	v_cvt_pk_bf16_f32 v181, v182, v183
	v_add_u32_e32 v182, s16, v136
	s_lshl_b32 s8, s10, 6
	v_ashrrev_i32_e32 v183, 31, v182
	s_ashr_i32 s9, s8, 31
	v_lshlrev_b64 v[182:183], 12, v[182:183]
	v_lshl_add_u64 v[182:183], s[14:15], 0, v[182:183]
	s_lshl_b64 s[8:9], s[8:9], 1
	v_lshl_add_u64 v[182:183], v[182:183], 0, s[8:9]
	v_lshl_add_u64 v[182:183], v[182:183], 0, v[134:135]
	ds_read2_b32 v[184:185], v137 offset0:8 offset1:73
	global_store_dwordx4 v[182:183], v[178:181], off
	s_andn2_b64 vcc, exec, s[6:7]
	s_mov_b64 s[6:7], -1
	s_waitcnt lgkmcnt(0)
	v_cvt_pk_bf16_f32 v178, v184, v185
	ds_read2_b32 v[180:181], v137 offset0:138 offset1:203
	s_waitcnt lgkmcnt(0)
	v_cvt_pk_bf16_f32 v179, v180, v181
	ds_read2_b32 v[180:181], v146 offset0:12 offset1:77
	s_waitcnt lgkmcnt(0)
	v_cvt_pk_bf16_f32 v180, v180, v181
	ds_read2_b32 v[182:183], v146 offset0:142 offset1:207
	s_waitcnt lgkmcnt(0)
	v_cvt_pk_bf16_f32 v181, v182, v183
	v_add_u32_e32 v182, s16, v138
	v_ashrrev_i32_e32 v183, 31, v182
	v_lshlrev_b64 v[182:183], 12, v[182:183]
	v_lshl_add_u64 v[182:183], s[14:15], 0, v[182:183]
	v_lshl_add_u64 v[182:183], v[182:183], 0, s[8:9]
	v_lshl_add_u64 v[182:183], v[182:183], 0, v[134:135]
	ds_read2_b32 v[184:185], v137 offset0:16 offset1:81
	global_store_dwordx4 v[182:183], v[178:181], off
	s_waitcnt lgkmcnt(0)
	s_nop 0
	v_cvt_pk_bf16_f32 v178, v184, v185
	ds_read2_b32 v[180:181], v137 offset0:146 offset1:211
	s_waitcnt lgkmcnt(0)
	v_cvt_pk_bf16_f32 v179, v180, v181
	ds_read2_b32 v[180:181], v146 offset0:20 offset1:85
	s_waitcnt lgkmcnt(0)
	v_cvt_pk_bf16_f32 v180, v180, v181
	ds_read2_b32 v[182:183], v146 offset0:150 offset1:215
	s_waitcnt lgkmcnt(0)
	v_cvt_pk_bf16_f32 v181, v182, v183
	v_add_u32_e32 v182, s16, v139
	v_ashrrev_i32_e32 v183, 31, v182
	v_lshlrev_b64 v[182:183], 12, v[182:183]
	v_lshl_add_u64 v[182:183], s[14:15], 0, v[182:183]
	v_lshl_add_u64 v[182:183], v[182:183], 0, s[8:9]
	v_lshl_add_u64 v[182:183], v[182:183], 0, v[134:135]
	ds_read2_b32 v[184:185], v137 offset0:24 offset1:89
	global_store_dwordx4 v[182:183], v[178:181], off
	s_waitcnt lgkmcnt(0)
	s_nop 0
	v_cvt_pk_bf16_f32 v178, v184, v185
	ds_read2_b32 v[180:181], v137 offset0:154 offset1:219
	s_waitcnt lgkmcnt(0)
	v_cvt_pk_bf16_f32 v179, v180, v181
	ds_read2_b32 v[180:181], v146 offset0:28 offset1:93
	s_waitcnt lgkmcnt(0)
	v_cvt_pk_bf16_f32 v180, v180, v181
	ds_read2_b32 v[182:183], v146 offset0:158 offset1:223
	s_waitcnt lgkmcnt(0)
; #define LAS __attribute__((address_space(3)))
; #define LDS_WAIT() asm volatile("s_waitcnt lgkmcnt(0)" ::: "memory")
; __device__ __forceinline__ unsigned pk2(float lo, float hi) { return pg8::cvt_pk_bf16(lo, hi); }
; __device__ __forceinline__ void tr_load(const TJob& j, f32x4 (&v)[16], int lane) {
;     const int nq = lane & 15, kr = lane >> 4;
;     const float* src = j.W + (size_t)(64 * j.kb + kr) * j.N + 64 * j.nb + 4 * nq;
; #pragma unroll
;     for (int i = 0; i < 16; ++i) v[i] = __builtin_nontemporal_load((const f32x4*)(src + (size_t)(4 * i) * j.N));
; }
; __device__ __forceinline__ void tr_store(const TJob& j, const f32x4 (&v)[16], LAS float* scr, int lane) {
;     const int k0 = 64 * j.kb, nq = lane & 15, kr = lane >> 4;
; #pragma unroll
;     for (int i = 0; i < 16; ++i) { LAS float* d = scr + (4 * i + kr) * TP + 4 * nq; const float sc = j.kscale ? j.kscale[k0 + 4 * i + kr] : 1.f; d[0] = v[i].x * sc; d[1] = v[i].y * sc; d[2] = v[i].z * sc; d[3] = v[i].w * sc; }
;     LDS_WAIT(); asm volatile("" ::: "memory");
;     const int c = lane & 7;
; #pragma unroll
;     for (int jj = 0; jj < 8; ++jj) { const int n = (lane >> 3) + 8 * jj; const LAS float* q = scr + (8 * c) * TP + n; const int nd = j.perm ? 32 * ((n >> 4) & 1) + 8 * ((n >> 2) & 3) + 4 * (n >> 5) + (n & 3) : n;
;         v4u o; o.x = pk2(q[0 * TP], q[1 * TP]); o.y = pk2(q[2 * TP], q[3 * TP]); o.z = pk2(q[4 * TP], q[5 * TP]); o.w = pk2(q[6 * TP], q[7 * TP]);
;         *(v4u*)(j.WT + (size_t)(j.drow0 + nd) * j.K + k0 + 8 * c) = o; }
;     LDS_WAIT(); asm volatile("" ::: "memory");
; }
; __global__ void __launch_bounds__(NWAVES * 64, 2) fwd_kernel(Args a) {
;     ...
;                     const int itb = it + NGW; TJob jb; const bool hb = itb < I_IN; if (hb) { jb = job0(itb, a.in[3], a.in[6], a.in[8], a.in[10], a.in[13], a.in[14], win_t, wc_t, qb_t, kvb_t, mla_t, wo_t); tr_load(jb, vb, lane); }
;                     tr_store(ja, va, scr, lane); if (!hb) break;
;                     const int itc = itb + NGW; const bool hc = itc < I_IN; if (hc) { ja = job0(itc, a.in[3], a.in[6], a.in[8], a.in[10], a.in[13], a.in[14], win_t, wc_t, qb_t, kvb_t, mla_t, wo_t); tr_load(ja, va, lane); }
	v_cvt_pk_bf16_f32 v181, v182, v183
	v_add_u32_e32 v182, s16, v140
	v_ashrrev_i32_e32 v183, 31, v182
	v_lshlrev_b64 v[182:183], 12, v[182:183]
	v_lshl_add_u64 v[182:183], s[14:15], 0, v[182:183]
	v_lshl_add_u64 v[182:183], v[182:183], 0, s[8:9]
	v_lshl_add_u64 v[182:183], v[182:183], 0, v[134:135]
	ds_read2_b32 v[184:185], v137 offset0:32 offset1:97
	global_store_dwordx4 v[182:183], v[178:181], off
	s_waitcnt lgkmcnt(0)
	s_nop 0
	v_cvt_pk_bf16_f32 v178, v184, v185
	ds_read2_b32 v[180:181], v137 offset0:162 offset1:227
	s_waitcnt lgkmcnt(0)
	v_cvt_pk_bf16_f32 v179, v180, v181
	ds_read2_b32 v[180:181], v146 offset0:36 offset1:101
	s_waitcnt lgkmcnt(0)
	v_cvt_pk_bf16_f32 v180, v180, v181
	ds_read2_b32 v[182:183], v146 offset0:166 offset1:231
	s_waitcnt lgkmcnt(0)
	v_cvt_pk_bf16_f32 v181, v182, v183
	v_add_u32_e32 v182, s16, v141
	v_ashrrev_i32_e32 v183, 31, v182
	v_lshlrev_b64 v[182:183], 12, v[182:183]
	v_lshl_add_u64 v[182:183], s[14:15], 0, v[182:183]
	v_lshl_add_u64 v[182:183], v[182:183], 0, s[8:9]
	v_lshl_add_u64 v[182:183], v[182:183], 0, v[134:135]
	ds_read2_b32 v[184:185], v137 offset0:40 offset1:105
	global_store_dwordx4 v[182:183], v[178:181], off
	s_waitcnt lgkmcnt(0)
	s_nop 0
	v_cvt_pk_bf16_f32 v178, v184, v185
	ds_read2_b32 v[180:181], v137 offset0:170 offset1:235
	s_waitcnt lgkmcnt(0)
	v_cvt_pk_bf16_f32 v179, v180, v181
	ds_read2_b32 v[180:181], v146 offset0:44 offset1:109
	s_waitcnt lgkmcnt(0)
	v_cvt_pk_bf16_f32 v180, v180, v181
	ds_read2_b32 v[182:183], v146 offset0:174 offset1:239
	s_waitcnt lgkmcnt(0)
	v_cvt_pk_bf16_f32 v181, v182, v183
	v_add_u32_e32 v182, s16, v142
	v_ashrrev_i32_e32 v183, 31, v182
	v_lshlrev_b64 v[182:183], 12, v[182:183]
	v_lshl_add_u64 v[182:183], s[14:15], 0, v[182:183]
	v_lshl_add_u64 v[182:183], v[182:183], 0, s[8:9]
	v_lshl_add_u64 v[182:183], v[182:183], 0, v[134:135]
	ds_read2_b32 v[184:185], v137 offset0:48 offset1:113
	global_store_dwordx4 v[182:183], v[178:181], off
	s_waitcnt lgkmcnt(0)
	s_nop 0
	v_cvt_pk_bf16_f32 v178, v184, v185
	ds_read2_b32 v[180:181], v137 offset0:178 offset1:243
	s_waitcnt lgkmcnt(0)
	v_cvt_pk_bf16_f32 v179, v180, v181
	ds_read2_b32 v[180:181], v146 offset0:52 offset1:117
	s_waitcnt lgkmcnt(0)
	v_cvt_pk_bf16_f32 v180, v180, v181
	ds_read2_b32 v[182:183], v146 offset0:182 offset1:247
	s_waitcnt lgkmcnt(0)
	v_cvt_pk_bf16_f32 v181, v182, v183
	v_add_u32_e32 v182, s16, v143
	v_ashrrev_i32_e32 v183, 31, v182
	v_lshlrev_b64 v[182:183], 12, v[182:183]
	v_lshl_add_u64 v[182:183], s[14:15], 0, v[182:183]
	v_lshl_add_u64 v[182:183], v[182:183], 0, s[8:9]
	v_lshl_add_u64 v[182:183], v[182:183], 0, v[134:135]
	ds_read2_b32 v[184:185], v137 offset0:56 offset1:121
	global_store_dwordx4 v[182:183], v[178:181], off
	s_waitcnt lgkmcnt(0)
	s_nop 0
	v_cvt_pk_bf16_f32 v178, v184, v185
	ds_read2_b32 v[180:181], v137 offset0:186 offset1:251
	s_waitcnt lgkmcnt(0)
	v_cvt_pk_bf16_f32 v179, v180, v181
	ds_read2_b32 v[180:181], v146 offset0:60 offset1:125
	s_waitcnt lgkmcnt(0)
	v_cvt_pk_bf16_f32 v180, v180, v181
	ds_read2_b32 v[182:183], v146 offset0:190 offset1:255
	s_waitcnt lgkmcnt(0)
	v_cvt_pk_bf16_f32 v181, v182, v183
	v_add_u32_e32 v182, s16, v144
	v_ashrrev_i32_e32 v183, 31, v182
	v_lshlrev_b64 v[182:183], 12, v[182:183]
	v_lshl_add_u64 v[182:183], s[14:15], 0, v[182:183]
	v_lshl_add_u64 v[182:183], v[182:183], 0, s[8:9]
	v_lshl_add_u64 v[182:183], v[182:183], 0, v[134:135]
	global_store_dwordx4 v[182:183], v[178:181], off
	s_waitcnt lgkmcnt(0)
	s_cbranch_vccnz .LBB0_9
	s_lshl_b32 s8, s13, 8
	s_and_b32 s9, s95, 31
	s_lshl_b32 s9, s9, 3
	s_add_i32 s8, s8, s9
	s_lshr_b32 s9, s95, 5
	s_add_i32 s8, s8, s9
	s_addk_i32 s8, 0x1000
	s_cmpk_gt_i32 s8, 0x109f
	s_cselect_b64 s[6:7], -1, 0
	s_and_b64 vcc, exec, s[6:7]
	s_cbranch_vccnz .LBB0_8
	s_mul_hi_i32 s9, s8, 0xf6603d99
	s_add_i32 s9, s9, s8
	s_lshr_b32 s10, s9, 31
	s_ashr_i32 s9, s9, 7
	s_add_i32 s10, s9, s10
	s_mul_i32 s9, s10, 0x85
	s_sub_i32 s9, s8, s9
	s_lshl_b32 s36, s9, 6
	s_sub_i32 s16, s36, 64
	s_cmpk_lg_i32 s9, 0x44
	s_cselect_b32 s16, s16, 0x2100
	s_cmpk_lt_i32 s9, 0x44
	v_lshl_or_b32 v4, s10, 6, v133
	v_mov_b64_e32 v[2:3], s[58:59]
	s_cselect_b32 s16, s36, s16
	v_mad_i64_i32 v[2:3], s[38:39], v4, s11, v[2:3]
	s_ashr_i32 s37, s36, 31
	v_lshl_add_u64 v[2:3], s[36:37], 2, v[2:3]
	v_lshlrev_b32_e32 v4, 2, v132
	v_mov_b32_e32 v5, v135
	v_lshl_add_u64 v[98:99], v[2:3], 0, v[4:5]
	v_add_co_u32_e32 v6, vcc, s17, v98
	s_mov_b32 s36, s8
	s_nop 0
	v_addc_co_u32_e32 v7, vcc, 0, v99, vcc
	v_add_co_u32_e32 v10, vcc, s18, v98
	global_load_dwordx4 v[2:5], v[98:99], off nt
	s_nop 0
	global_load_dwordx4 v[6:9], v[6:7], off offset:1024 nt
	v_addc_co_u32_e32 v11, vcc, 0, v99, vcc
	v_add_co_u32_e32 v14, vcc, s19, v98
	s_nop 1
	v_addc_co_u32_e32 v15, vcc, 0, v99, vcc
	v_add_co_u32_e32 v18, vcc, s20, v98
	global_load_dwordx4 v[10:13], v[10:11], off offset:2048 nt
	s_nop 0
	global_load_dwordx4 v[14:17], v[14:15], off offset:3072 nt
	v_addc_co_u32_e32 v19, vcc, 0, v99, vcc
	v_add_co_u32_e32 v22, vcc, s21, v98
	s_nop 1
	v_addc_co_u32_e32 v23, vcc, 0, v99, vcc
	v_add_co_u32_e32 v34, vcc, s22, v98
	global_load_dwordx4 v[18:21], v[18:19], off nt
	s_nop 0
	global_load_dwordx4 v[22:25], v[22:23], off offset:1024 nt
	v_addc_co_u32_e32 v35, vcc, 0, v99, vcc
	v_add_co_u32_e32 v38, vcc, s23, v98
	s_nop 1
	v_addc_co_u32_e32 v39, vcc, 0, v99, vcc
	v_add_co_u32_e32 v50, vcc, s24, v98
	global_load_dwordx4 v[34:37], v[34:35], off offset:2048 nt
	s_nop 0
	global_load_dwordx4 v[38:41], v[38:39], off offset:3072 nt
	v_addc_co_u32_e32 v51, vcc, 0, v99, vcc
	v_add_co_u32_e32 v54, vcc, s25, v98
	s_nop 1
	v_addc_co_u32_e32 v55, vcc, 0, v99, vcc
	v_add_co_u32_e32 v66, vcc, s26, v98
	global_load_dwordx4 v[50:53], v[50:51], off nt
	s_nop 0
	global_load_dwordx4 v[54:57], v[54:55], off offset:1024 nt
	v_addc_co_u32_e32 v67, vcc, 0, v99, vcc
	v_add_co_u32_e32 v70, vcc, s27, v98
	s_nop 1
	v_addc_co_u32_e32 v71, vcc, 0, v99, vcc
	v_add_co_u32_e32 v82, vcc, s33, v98
	global_load_dwordx4 v[66:69], v[66:67], off offset:2048 nt
	s_nop 0
	global_load_dwordx4 v[70:73], v[70:71], off offset:3072 nt
	v_addc_co_u32_e32 v83, vcc, 0, v99, vcc
	v_add_co_u32_e32 v86, vcc, 0x1b0000, v98
	s_nop 1
	v_addc_co_u32_e32 v87, vcc, 0, v99, vcc
	v_add_co_u32_e32 v100, vcc, 0x1d1000, v98
	global_load_dwordx4 v[82:85], v[82:83], off nt
	s_nop 0
	global_load_dwordx4 v[86:89], v[86:87], off offset:1024 nt
	v_addc_co_u32_e32 v101, vcc, 0, v99, vcc
	v_add_co_u32_e32 v102, vcc, 0x1f2000, v98
	s_nop 1
	v_addc_co_u32_e32 v103, vcc, 0, v99, vcc
	global_load_dwordx4 v[98:101], v[100:101], off offset:2048 nt
	s_nop 0
	global_load_dwordx4 v[102:105], v[102:103], off offset:3072 nt
	s_branch .LBB0_8

; #define LAS __attribute__((address_space(3)))
; #define LDS_WAIT() asm volatile("s_waitcnt lgkmcnt(0)" ::: "memory")
; __device__ __forceinline__ unsigned pk2(float lo, float hi) { return pg8::cvt_pk_bf16(lo, hi); }
; __device__ __forceinline__ void tr_store(const TJob& j, const f32x4 (&v)[16], LAS float* scr, int lane) {
;     const int k0 = 64 * j.kb, nq = lane & 15, kr = lane >> 4;
; #pragma unroll
;     for (int i = 0; i < 16; ++i) { LAS float* d = scr + (4 * i + kr) * TP + 4 * nq; const float sc = j.kscale ? j.kscale[k0 + 4 * i + kr] : 1.f; d[0] = v[i].x * sc; d[1] = v[i].y * sc; d[2] = v[i].z * sc; d[3] = v[i].w * sc; }
;     LDS_WAIT(); asm volatile("" ::: "memory");
;     const int c = lane & 7;
; #pragma unroll
;     for (int jj = 0; jj < 8; ++jj) { const int n = (lane >> 3) + 8 * jj; const LAS float* q = scr + (8 * c) * TP + n; const int nd = j.perm ? 32 * ((n >> 4) & 1) + 8 * ((n >> 2) & 3) + 4 * (n >> 5) + (n & 3) : n;
;         v4u o; o.x = pk2(q[0 * TP], q[1 * TP]); o.y = pk2(q[2 * TP], q[3 * TP]); o.z = pk2(q[4 * TP], q[5 * TP]); o.w = pk2(q[6 * TP], q[7 * TP]);
;         *(v4u*)(j.WT + (size_t)(j.drow0 + nd) * j.K + k0 + 8 * c) = o; }
;     LDS_WAIT(); asm volatile("" ::: "memory");
; }
.LBB0_728:
	s_waitcnt vmcnt(0)
	v_pk_mul_f32 v[176:177], v[84:85], v[132:133] op_sel_hi:[1,0]
	v_add_u32_e32 v175, 0x3cf0, v136
	ds_write2_b32 v175, v176, v177 offset1:1
	v_pk_mul_f32 v[132:133], v[86:87], v[132:133] op_sel_hi:[1,0]
	v_add_u32_e32 v176, 0x3cf8, v136
	ds_write2_b32 v176, v132, v133 offset1:1
	v_add_u32_e32 v182, s35, v137
	s_waitcnt lgkmcnt(0)
	v_ashrrev_i32_e32 v183, 31, v182
	s_ashr_i32 s9, s8, 31
	v_lshlrev_b64 v[182:183], 12, v[182:183]
	ds_read2_b32 v[132:133], v138 offset1:65
	s_lshl_b64 s[0:1], s[8:9], 1
	v_lshl_add_u64 v[182:183], s[38:39], 0, v[182:183]
	s_waitcnt lgkmcnt(0)
	v_cvt_pk_bf16_f32 v178, v132, v133
	ds_read2_b32 v[132:133], v138 offset0:130 offset1:195
	v_add_u32_e32 v146, 0x400, v138
	v_lshl_add_u64 v[182:183], v[182:183], 0, s[0:1]
	s_waitcnt lgkmcnt(0)
	v_cvt_pk_bf16_f32 v179, v132, v133
	ds_read2_b32 v[132:133], v146 offset0:4 offset1:69
	v_lshl_add_u64 v[182:183], v[182:183], 0, v[130:131]
	s_waitcnt lgkmcnt(0)
	v_cvt_pk_bf16_f32 v180, v132, v133
	ds_read2_b32 v[132:133], v146 offset0:134 offset1:199
	s_waitcnt lgkmcnt(0)
	v_cvt_pk_bf16_f32 v181, v132, v133
	global_store_dwordx4 v[182:183], v[178:181], off
	v_add_u32_e32 v182, s35, v139
	v_ashrrev_i32_e32 v183, 31, v182
	v_lshlrev_b64 v[182:183], 12, v[182:183]
	ds_read2_b32 v[132:133], v138 offset0:8 offset1:73
	v_lshl_add_u64 v[182:183], s[38:39], 0, v[182:183]
	s_waitcnt lgkmcnt(0)
	v_cvt_pk_bf16_f32 v178, v132, v133
	ds_read2_b32 v[132:133], v138 offset0:138 offset1:203
	v_lshl_add_u64 v[182:183], v[182:183], 0, s[0:1]
	s_waitcnt lgkmcnt(0)
	v_cvt_pk_bf16_f32 v179, v132, v133
	ds_read2_b32 v[132:133], v146 offset0:12 offset1:77
	v_lshl_add_u64 v[182:183], v[182:183], 0, v[130:131]
	s_waitcnt lgkmcnt(0)
	v_cvt_pk_bf16_f32 v180, v132, v133
	ds_read2_b32 v[132:133], v146 offset0:142 offset1:207
	s_waitcnt lgkmcnt(0)
	v_cvt_pk_bf16_f32 v181, v132, v133
	global_store_dwordx4 v[182:183], v[178:181], off
	v_add_u32_e32 v182, s35, v140
	v_ashrrev_i32_e32 v183, 31, v182
	v_lshlrev_b64 v[182:183], 12, v[182:183]
	ds_read2_b32 v[132:133], v138 offset0:16 offset1:81
	v_lshl_add_u64 v[182:183], s[38:39], 0, v[182:183]
	s_waitcnt lgkmcnt(0)
	v_cvt_pk_bf16_f32 v178, v132, v133
	ds_read2_b32 v[132:133], v138 offset0:146 offset1:211
	v_lshl_add_u64 v[182:183], v[182:183], 0, s[0:1]
	s_waitcnt lgkmcnt(0)
	v_cvt_pk_bf16_f32 v179, v132, v133
	ds_read2_b32 v[132:133], v146 offset0:20 offset1:85
	v_lshl_add_u64 v[182:183], v[182:183], 0, v[130:131]
	s_waitcnt lgkmcnt(0)
	v_cvt_pk_bf16_f32 v180, v132, v133
	ds_read2_b32 v[132:133], v146 offset0:150 offset1:215
	s_waitcnt lgkmcnt(0)
	v_cvt_pk_bf16_f32 v181, v132, v133
	global_store_dwordx4 v[182:183], v[178:181], off
	v_add_u32_e32 v182, s35, v141
	v_ashrrev_i32_e32 v183, 31, v182
	v_lshlrev_b64 v[182:183], 12, v[182:183]
	ds_read2_b32 v[132:133], v138 offset0:24 offset1:89
	v_lshl_add_u64 v[182:183], s[38:39], 0, v[182:183]
	s_waitcnt lgkmcnt(0)
	v_cvt_pk_bf16_f32 v178, v132, v133
	ds_read2_b32 v[132:133], v138 offset0:154 offset1:219
	v_lshl_add_u64 v[182:183], v[182:183], 0, s[0:1]
	s_waitcnt lgkmcnt(0)
	v_cvt_pk_bf16_f32 v179, v132, v133
	ds_read2_b32 v[132:133], v146 offset0:28 offset1:93
	v_lshl_add_u64 v[182:183], v[182:183], 0, v[130:131]
	s_waitcnt lgkmcnt(0)
	v_cvt_pk_bf16_f32 v180, v132, v133
	ds_read2_b32 v[132:133], v146 offset0:158 offset1:223
	s_waitcnt lgkmcnt(0)
	v_cvt_pk_bf16_f32 v181, v132, v133
	global_store_dwordx4 v[182:183], v[178:181], off
	v_add_u32_e32 v182, s35, v142
	v_ashrrev_i32_e32 v183, 31, v182
	v_lshlrev_b64 v[182:183], 12, v[182:183]
	ds_read2_b32 v[132:133], v138 offset0:32 offset1:97
	v_lshl_add_u64 v[182:183], s[38:39], 0, v[182:183]
	s_waitcnt lgkmcnt(0)
	v_cvt_pk_bf16_f32 v178, v132, v133
	ds_read2_b32 v[132:133], v138 offset0:162 offset1:227
	v_lshl_add_u64 v[182:183], v[182:183], 0, s[0:1]
	s_waitcnt lgkmcnt(0)
	v_cvt_pk_bf16_f32 v179, v132, v133
	ds_read2_b32 v[132:133], v146 offset0:36 offset1:101
	v_lshl_add_u64 v[182:183], v[182:183], 0, v[130:131]
	s_waitcnt lgkmcnt(0)
	v_cvt_pk_bf16_f32 v180, v132, v133
	ds_read2_b32 v[132:133], v146 offset0:166 offset1:231
	s_waitcnt lgkmcnt(0)
	v_cvt_pk_bf16_f32 v181, v132, v133
	global_store_dwordx4 v[182:183], v[178:181], off
	v_add_u32_e32 v182, s35, v143
	v_ashrrev_i32_e32 v183, 31, v182
	v_lshlrev_b64 v[182:183], 12, v[182:183]
	ds_read2_b32 v[132:133], v138 offset0:40 offset1:105
	v_lshl_add_u64 v[182:183], s[38:39], 0, v[182:183]
	s_waitcnt lgkmcnt(0)
	v_cvt_pk_bf16_f32 v178, v132, v133
	ds_read2_b32 v[132:133], v138 offset0:170 offset1:235
	v_lshl_add_u64 v[182:183], v[182:183], 0, s[0:1]
	s_waitcnt lgkmcnt(0)
	v_cvt_pk_bf16_f32 v179, v132, v133
	ds_read2_b32 v[132:133], v146 offset0:44 offset1:109
	v_lshl_add_u64 v[182:183], v[182:183], 0, v[130:131]
	s_waitcnt lgkmcnt(0)
	v_cvt_pk_bf16_f32 v180, v132, v133
	ds_read2_b32 v[132:133], v146 offset0:174 offset1:239
	s_waitcnt lgkmcnt(0)
	v_cvt_pk_bf16_f32 v181, v132, v133
	global_store_dwordx4 v[182:183], v[178:181], off
	v_add_u32_e32 v182, s35, v144
	v_ashrrev_i32_e32 v183, 31, v182
	v_lshlrev_b64 v[182:183], 12, v[182:183]
	ds_read2_b32 v[132:133], v138 offset0:48 offset1:113
	v_lshl_add_u64 v[182:183], s[38:39], 0, v[182:183]
	s_waitcnt lgkmcnt(0)
	v_cvt_pk_bf16_f32 v178, v132, v133
	ds_read2_b32 v[132:133], v138 offset0:178 offset1:243
	v_lshl_add_u64 v[182:183], v[182:183], 0, s[0:1]
	s_waitcnt lgkmcnt(0)
	v_cvt_pk_bf16_f32 v179, v132, v133
	ds_read2_b32 v[132:133], v146 offset0:52 offset1:117
	v_lshl_add_u64 v[182:183], v[182:183], 0, v[130:131]
	s_waitcnt lgkmcnt(0)
	v_cvt_pk_bf16_f32 v180, v132, v133
	ds_read2_b32 v[132:133], v146 offset0:182 offset1:247
	s_waitcnt lgkmcnt(0)
	v_cvt_pk_bf16_f32 v181, v132, v133
	global_store_dwordx4 v[182:183], v[178:181], off
	v_add_u32_e32 v182, s35, v145
	v_ashrrev_i32_e32 v183, 31, v182
	v_lshlrev_b64 v[182:183], 12, v[182:183]
	ds_read2_b32 v[132:133], v138 offset0:56 offset1:121
	v_lshl_add_u64 v[182:183], s[38:39], 0, v[182:183]
	s_waitcnt lgkmcnt(0)
	v_cvt_pk_bf16_f32 v178, v132, v133
	ds_read2_b32 v[132:133], v138 offset0:186 offset1:251
	v_lshl_add_u64 v[182:183], v[182:183], 0, s[0:1]
	s_waitcnt lgkmcnt(0)
	v_cvt_pk_bf16_f32 v179, v132, v133
	ds_read2_b32 v[132:133], v146 offset0:60 offset1:125
	v_lshl_add_u64 v[182:183], v[182:183], 0, v[130:131]
	s_waitcnt lgkmcnt(0)
	v_cvt_pk_bf16_f32 v180, v132, v133
	ds_read2_b32 v[132:133], v146 offset0:190 offset1:255
	s_waitcnt lgkmcnt(0)
	v_cvt_pk_bf16_f32 v181, v132, v133
	global_store_dwordx4 v[182:183], v[178:181], off
	s_waitcnt lgkmcnt(0)
	s_andn2_b64 vcc, exec, s[6:7]
	s_mov_b64 s[6:7], 0
	s_cbranch_vccnz .LBB0_701
; __device__ __forceinline__ void tr_load(const TJob& j, f32x4 (&v)[16], int lane) {
;     const int nq = lane & 15, kr = lane >> 4;
;     const float* src = j.W + (size_t)(64 * j.kb + kr) * j.N + 64 * j.nb + 4 * nq;
; #pragma unroll
;     for (int i = 0; i < 16; ++i) v[i] = __builtin_nontemporal_load((const f32x4*)(src + (size_t)(4 * i) * j.N));
; }
; __device__ __forceinline__ TJob job8(int it, const float* w_up, const float* w_dn, const float* ln2g, bf16* up_t, bf16* down_t) {
;     int r = it; TJob j; j.perm = 0;
;     if (r < I_UP) { const int nblk = 2 * DFF / 64; j.kb = r / nblk; j.nb = r % nblk; const int n0 = 64 * j.nb, hf = n0 >= DFF ? 1 : 0, jc = n0 - hf * DFF;
;         j.drow0 = 256 * (jc / 128) + 128 * hf + (jc % 128); j.W = w_up; j.K = DM; j.N = 2 * DFF; j.WT = up_t; j.kscale = ln2g; return j; } r -= I_UP;
	s_sub_i32 s41, s41, s12
	s_sub_i32 s41, s41, s90
	s_lshl_b32 s41, s41, 8
	s_lshr_b32 s0, s90, 3
	s_and_b32 s1, s0, 31
	s_lshl_b32 s1, s1, 3
	s_lshr_b32 s0, s0, 5
	s_add_i32 s0, s0, s1
	s_add_i32 s41, s41, s0
	s_addk_i32 s41, 0x1000
	s_cmpk_lt_i32 s41, 0x1600
	s_cselect_b64 s[6:7], -1, 0
	s_cmpk_gt_i32 s41, 0x15ff
	s_cbranch_scc1 .LBB0_731
	s_mul_hi_i32 s0, s41, 0x2e8ba2e9
	s_lshr_b32 s1, s0, 31
	s_ashr_i32 s0, s0, 5
	s_add_i32 s13, s0, s1
	s_mul_i32 s0, s13, 0xb0
	s_sub_i32 s1, s41, s0
	v_readlane_b32 s56, v254, 0
	s_lshl_b32 s0, s1, 6
	v_readlane_b32 s57, v254, 1
	s_cmpk_gt_i32 s1, 0x57
	v_lshl_or_b32 v2, s13, 6, v135
	v_mov_b64_e32 v[0:1], s[56:57]
	s_cselect_b32 s10, 0xea00, 0
	s_cselect_b32 s11, 0x80, 0
	v_mad_i64_i32 v[0:1], s[8:9], v2, s14, v[0:1]
	s_ashr_i32 s1, s0, 31
	v_lshl_add_u64 v[0:1], s[0:1], 2, v[0:1]
	v_lshlrev_b32_e32 v2, 2, v128
	v_mov_b32_e32 v3, v131
	v_lshl_add_u64 v[72:73], v[0:1], 0, v[2:3]
	v_add_co_u32_e32 v4, vcc, s15, v72
	s_add_i32 s0, s10, s0
	s_nop 0
	v_addc_co_u32_e32 v5, vcc, 0, v73, vcc
	v_add_co_u32_e32 v8, vcc, s18, v72
	global_load_dwordx4 v[0:3], v[72:73], off nt
	s_nop 0
	global_load_dwordx4 v[4:7], v[4:5], off nt
	v_addc_co_u32_e32 v9, vcc, 0, v73, vcc
	v_add_co_u32_e32 v12, vcc, s19, v72
	s_sext_i32_i16 s1, s0
	s_nop 0
	v_addc_co_u32_e32 v13, vcc, 0, v73, vcc
	v_add_co_u32_e32 v16, vcc, s20, v72
	global_load_dwordx4 v[8:11], v[8:9], off nt
	s_nop 0
	global_load_dwordx4 v[12:15], v[12:13], off nt
	v_addc_co_u32_e32 v17, vcc, 0, v73, vcc
	v_add_co_u32_e32 v20, vcc, s21, v72
	s_bfe_u32 s1, s1, 0x70018
	s_nop 0
	v_addc_co_u32_e32 v21, vcc, 0, v73, vcc
	v_add_co_u32_e32 v24, vcc, s22, v72
	global_load_dwordx4 v[16:19], v[16:17], off nt
	s_nop 0
	global_load_dwordx4 v[20:23], v[20:21], off nt
	v_addc_co_u32_e32 v25, vcc, 0, v73, vcc
	v_add_co_u32_e32 v28, vcc, s23, v72
	s_add_i32 s1, s0, s1
	s_nop 0
	v_addc_co_u32_e32 v29, vcc, 0, v73, vcc
	v_add_co_u32_e32 v32, vcc, s24, v72
	global_load_dwordx4 v[24:27], v[24:25], off nt
	s_nop 0
	global_load_dwordx4 v[28:31], v[28:29], off nt
	v_addc_co_u32_e32 v33, vcc, 0, v73, vcc
	v_add_co_u32_e32 v36, vcc, s25, v72
	s_sext_i32_i16 s8, s1
	s_nop 0
	v_addc_co_u32_e32 v37, vcc, 0, v73, vcc
	v_add_co_u32_e32 v40, vcc, s26, v72
	global_load_dwordx4 v[32:35], v[32:33], off nt
	s_nop 0
	global_load_dwordx4 v[36:39], v[36:37], off nt
	v_addc_co_u32_e32 v41, vcc, 0, v73, vcc
	v_add_co_u32_e32 v44, vcc, s27, v72
	s_and_b32 s1, s1, 0xff80
	s_nop 0
	v_addc_co_u32_e32 v45, vcc, 0, v73, vcc
	v_add_co_u32_e32 v48, vcc, s33, v72
	global_load_dwordx4 v[40:43], v[40:41], off nt
	s_nop 0
	global_load_dwordx4 v[44:47], v[44:45], off nt
	v_addc_co_u32_e32 v49, vcc, 0, v73, vcc
	v_add_co_u32_e32 v52, vcc, 0x23c000, v72
	s_sub_i32 s0, s0, s1
	s_nop 0
	v_addc_co_u32_e32 v53, vcc, 0, v73, vcc
	v_add_co_u32_e32 v74, vcc, 0x268000, v72
	global_load_dwordx4 v[48:51], v[48:49], off nt
	s_nop 0
	global_load_dwordx4 v[52:55], v[52:53], off nt
	v_addc_co_u32_e32 v75, vcc, 0, v73, vcc
	v_add_co_u32_e32 v84, vcc, 0x294000, v72
	s_lshl_b32 s8, s8, 1
	s_nop 0
	v_addc_co_u32_e32 v85, vcc, 0, v73, vcc
	global_load_dwordx4 v[72:75], v[74:75], off nt
	s_nop 0
	global_load_dwordx4 v[84:87], v[84:85], off nt
	s_sext_i32_i16 s0, s0
	s_and_b32 s8, s8, 0xffffff00
	s_add_i32 s0, s11, s0
	s_add_i32 s35, s0, s8
	v_readlane_b32 s58, v254, 2
	v_readlane_b32 s59, v254, 3
	v_readlane_b32 s60, v254, 4
	v_readlane_b32 s61, v254, 5
	v_readlane_b32 s62, v254, 6
	v_readlane_b32 s63, v254, 7
